# SwiGLU phase_init: rs table split across wave halves (3 serialized round trips instead of 6)
# speedup vs baseline: 1.0087x; 1.0087x over previous
; #define PG8_LAS __attribute__((address_space(3)))
;     __host__ __device__ bool next(int i, Unit& u) const { if (i != 0 || c < 0 || c >= n) return false; u.pm = c / nN; u.pn = c - u.pm * nN; return true; }
; __device__ __forceinline__ float part8(const float* p) { const f32x4 a = *(const f32x4*)p, b = *(const f32x4*)(p + 4); return ((a[0] + a[1]) + (a[2] + a[3])) + ((b[0] + b[1]) + (b[2] + b[3])); }
;     template <class Sched> __device__ __forceinline__ void phase_init(const Sched& S, PG8_LAS float* tab, int tid) const {
;         Unit u;
;         for (int i = 0; S.next(i, u); ++i)
;             if (tid < 256) tab[i * 256 + tid] = __builtin_amdgcn_rsqf(part8(ssq + (size_t)(u.pm * BM + tid) * 8) * (1.0f / 2048.0f) + EPS);
;     }
; template <class Epi, class Sched, bool ALIGN_EPI, bool SP2, int KK, int LDA, int APN>
; __device__ __forceinline__ void gemm_phase(PG8_LAS unsigned char* lds, const Gemm g, const Sched& S, const Epi& E, const int wid) {
;     ...
;     Unit cur, nxt; int ui = 0;
;     if (!S.next(0, cur)) return;
;     PG8_LAS float* etab = (PG8_LAS float*)(lds + STAGE_BYTES);
;     if constexpr (Epi::HAS_INIT) { E.phase_init(S, etab, tid); asm volatile("s_waitcnt vmcnt(0) lgkmcnt(0)" ::: "memory"); __builtin_amdgcn_s_barrier(); asm volatile("" ::: "memory"); }
.LBB0_205:
	v_readlane_b32 s8, v254, 0
	v_writelane_b32 v255, s2, 25
	v_readlane_b32 s9, v254, 1
	v_readlane_b32 s10, v254, 2
	v_writelane_b32 v255, s3, 26
	s_mov_b32 s2, s72
	s_mov_b32 s40, s73
	s_mov_b64 s[16:17], s[8:9]
	s_mov_b32 s12, s10
	s_mul_i32 s0, s56, 0x9c80000
	v_writelane_b32 v255, s0, 27
	s_add_u32 s0, s16, s0
	s_addc_u32 s1, s17, 0
	v_readlane_b32 s11, v254, 3
	s_add_u32 s10, s0, 0x900000
	s_addc_u32 s11, s1, 0
	s_mul_i32 s0, s56, 0x30000
	s_mov_b32 s1, s77
	v_writelane_b32 v255, s0, 28
	s_ashr_i32 s9, s40, 2
	s_lshl_b32 s48, s40, 10
	v_writelane_b32 v255, s1, 29
	s_lshl_b32 s0, s40, 5
	s_and_b32 s41, s0, 0x60
	s_lshl_b32 s8, s9, 6
	s_lshl_b32 s7, s9, 13
	s_lshr_b32 s6, s41, 3
	s_ashr_i32 s3, s2, 31
	v_mov_b32_e32 v8, v211
	s_cmpk_gt_i32 s2, 0x57f
	s_cbranch_scc1 .LBB0_227
	v_readlane_b32 s0, v255, 28
	v_readlane_b32 s1, v255, 29
	s_lshl_b64 s[0:1], s[0:1], 2
	s_add_u32 s0, s16, s0
	s_addc_u32 s1, s17, s1
	s_add_u32 s14, s0, 0x23a00000
	s_addc_u32 s15, s1, 0
	s_lshl_b32 s18, s40, 8
	s_add_i32 s18, s18, 0
	v_lshl_add_u32 v0, s40, 6, v8
	s_movk_i32 s0, 0x100
	s_add_i32 s18, s18, 0x20000
	s_ashr_i32 s13, s12, 31
	v_cmp_gt_i32_e64 s[0:1], s0, v0
	v_lshl_add_u32 v1, v8, 2, s18
	s_mov_b64 s[18:19], s[2:3]
	s_and_b32 s99, s40, 3
	v_lshl_add_u32 v15, s99, 6, v8
	s_lshl_b32 s100, s99, 8
	s_add_i32 s100, s100, 0x20000
	v_lshl_add_u32 v14, v8, 2, s100
	s_lshr_b32 s99, s40, 2
	s_branch .LBB0_209
.LBB0_207:
	s_or_b64 exec, exec, s[26:27]
	s_add_u32 s18, s18, s12
	v_add_u32_e32 v1, 0x400, v1
	s_addc_u32 s19, s19, s13
	v_add_u32_e32 v14, 0x400, v14
	s_xor_b32 s99, s99, 1
	s_mov_b64 s[26:27], 0

; #define PG8_LAS __attribute__((address_space(3)))
;     __host__ __device__ bool next(int i, Unit& u) const { if (i != 0 || c < 0 || c >= n) return false; u.pm = c / nN; u.pn = c - u.pm * nN; return true; }
; __device__ __forceinline__ float part8(const float* p) { const f32x4 a = *(const f32x4*)p, b = *(const f32x4*)(p + 4); return ((a[0] + a[1]) + (a[2] + a[3])) + ((b[0] + b[1]) + (b[2] + b[3])); }
;     __host__ __device__ bool next(int i, Unit& u) const {
;         const long L = (long)i * G + c; if (L >= nwg) return false;
;         int wgid = (int)L; { const int q = nwg / NXCD, r = nwg % NXCD, xcd = wgid % NXCD, off = wgid / NXCD; wgid = (xcd < r ? xcd * (q + 1) : r * (q + 1) + (xcd - r) * q) + off; }
;         const int nig = WGM * nN, gid = wgid / nig, fm = gid * WGM, gsz = (nM - fm) < WGM ? (nM - fm) : WGM;
;         u.pm = fm + ((wgid % nig) % gsz); u.pn = (wgid % nig) / gsz; return true;
;     template <class Sched> __device__ __forceinline__ void phase_init(const Sched& S, PG8_LAS float* tab, int tid) const {
;         Unit u;
;         for (int i = 0; S.next(i, u); ++i)
;             if (tid < 256) tab[i * 256 + tid] = __builtin_amdgcn_rsqf(part8(ssq + (size_t)(u.pm * BM + tid) * 8) * (1.0f / 2048.0f) + EPS);
;     }
.LBB0_209:
	v_cmp_gt_i64_e32 vcc, s[18:19], v[194:195]
	s_mov_b64 s[26:27], -1
	s_cbranch_vccnz .LBB0_208
	s_mov_b64 s[26:27], exec
	s_bitcmp1_b32 s99, 0
	s_cbranch_scc1 .LBB0_207
	s_ashr_i32 s28, s18, 31
	s_lshr_b32 s28, s28, 29
	s_add_i32 s28, s18, s28
	s_ashr_i32 s29, s28, 3
	s_and_b32 s28, s28, -8
	s_sub_i32 s28, s18, s28
	s_cmp_lt_i32 s28, 0
	s_movk_i32 s30, 0xb1
	s_cselect_b32 s30, s30, 0xb0
	s_mul_i32 s28, s28, s30
	s_add_i32 s28, s28, s29
	s_mul_hi_i32 s29, s28, 0x2e8ba2e9
	s_lshr_b32 s30, s29, 31
	s_ashr_i32 s29, s29, 6
	s_add_i32 s29, s29, s30
	s_lshl_b32 s30, s29, 3
	s_sub_i32 s31, 32, s30
	s_min_i32 s31, s31, 8
	s_abs_i32 s31, s31
	v_cvt_f32_u32_e32 v2, s31
	s_sub_i32 s36, 0, s31
	s_mulk_i32 s29, 0x160
	s_sub_i32 s28, s28, s29
	v_rcp_iflag_f32_e32 v2, v2
	s_ashr_i32 s29, s28, 31
	s_abs_i32 s28, s28
	v_mul_f32_e32 v2, 0x4f7ffffe, v2
	v_cvt_u32_f32_e32 v2, v2
	s_nop 0
	v_readfirstlane_b32 s37, v2
	s_mul_i32 s36, s36, s37
	s_mul_hi_u32 s36, s37, s36
	s_add_i32 s37, s37, s36
	s_mul_hi_u32 s36, s28, s37
	s_mul_i32 s36, s36, s31
	s_sub_i32 s28, s28, s36
	s_sub_i32 s36, s28, s31
	s_cmp_ge_u32 s28, s31
	s_cselect_b32 s28, s36, s28
	s_sub_i32 s36, s28, s31
	s_cmp_ge_u32 s28, s31
	s_cselect_b32 s28, s36, s28
	s_xor_b32 s28, s28, s29
	s_sub_i32 s28, s28, s29
	s_add_i32 s28, s28, s30
	v_lshl_add_u32 v2, s28, 8, v15
	v_ashrrev_i32_e32 v3, 31, v2
	v_lshlrev_b64 v[2:3], 5, v[2:3]
	v_lshl_add_u64 v[6:7], s[14:15], 0, v[2:3]
	flat_load_dwordx4 v[2:5], v[6:7]
	flat_load_dwordx4 v[10:13], v[6:7] offset:16
	s_waitcnt vmcnt(0) lgkmcnt(0)
	v_mov_b32_e32 v6, v2
	v_mov_b32_e32 v7, v10
	v_mov_b32_e32 v10, v3
	v_mov_b32_e32 v2, v4
	v_mov_b32_e32 v3, v12
	v_mov_b32_e32 v12, v5
	v_pk_add_f32 v[4:5], v[6:7], v[10:11]
	v_pk_add_f32 v[2:3], v[2:3], v[12:13]
	s_nop 0
	v_pk_add_f32 v[2:3], v[4:5], v[2:3]
	s_nop 0
	v_add_f32_e32 v2, v2, v3
	v_fmamk_f32 v2, v2, 0x3a000000, v220
	v_rsq_f32_e32 v2, v2
	ds_write_b32 v14, v2
	s_branch .LBB0_207

; #define PG8_LAS __attribute__((address_space(3)))
;     __host__ __device__ bool next(int i, Unit& u) const { if (i != 0 || c < 0 || c >= n) return false; u.pm = c / nN; u.pn = c - u.pm * nN; return true; }
; __device__ __forceinline__ float part8(const float* p) { const f32x4 a = *(const f32x4*)p, b = *(const f32x4*)(p + 4); return ((a[0] + a[1]) + (a[2] + a[3])) + ((b[0] + b[1]) + (b[2] + b[3])); }
;     template <class Sched> __device__ __forceinline__ void phase_init(const Sched& S, PG8_LAS float* tab, int tid) const {
;         Unit u;
;         for (int i = 0; S.next(i, u); ++i)
;             if (tid < 256) tab[i * 256 + tid] = __builtin_amdgcn_rsqf(part8(ssq + (size_t)(u.pm * BM + tid) * 8) * (1.0f / 2048.0f) + EPS);
;     }
; template <class Epi, class Sched, bool ALIGN_EPI, bool SP2, int KK, int LDA, int APN>
; __device__ __forceinline__ void gemm_phase(PG8_LAS unsigned char* lds, const Gemm g, const Sched& S, const Epi& E, const int wid) {
;     ...
;     if (!S.next(0, cur)) return;
;     PG8_LAS float* etab = (PG8_LAS float*)(lds + STAGE_BYTES);
;     if constexpr (Epi::HAS_INIT) { E.phase_init(S, etab, tid); asm volatile("s_waitcnt vmcnt(0) lgkmcnt(0)" ::: "memory"); __builtin_amdgcn_s_barrier(); asm volatile("" ::: "memory"); }
.LBB0_764:
	s_or_b64 exec, exec, s[0:1]
	v_readlane_b32 s0, v254, 0
	v_readlane_b32 s1, v254, 1
	v_readlane_b32 s2, v254, 2
	s_mov_b64 s[16:17], s[0:1]
	s_mov_b32 s6, s2
	s_mov_b32 s2, s72
	s_mov_b32 s34, s73
	s_waitcnt lgkmcnt(0)
	s_barrier
	v_mov_b32_e32 v8, v211
	s_cmpk_gt_i32 s2, 0x57f
	v_readlane_b32 s3, v254, 3
	s_cbranch_scc1 .LBB0_786
	s_lshl_b64 s[0:1], s[76:77], 2
	s_add_u32 s0, s16, s0
	s_addc_u32 s1, s17, s1
	s_add_u32 s14, s0, 0x23a00000
	s_addc_u32 s15, s1, 0
	s_lshl_b32 s8, s34, 8
	s_add_i32 s8, s8, 0
	v_lshl_add_u32 v0, s34, 6, v8
	s_ashr_i32 s3, s2, 31
	s_movk_i32 s0, 0x100
	s_add_i32 s8, s8, 0x20000
	s_ashr_i32 s7, s6, 31
	v_cmp_gt_i32_e64 s[0:1], s0, v0
	v_lshl_add_u32 v1, v8, 2, s8
	s_mov_b64 s[18:19], s[2:3]
	s_and_b32 s99, s34, 3
	v_lshl_add_u32 v15, s99, 6, v8
	s_lshl_b32 s100, s99, 8
	s_add_i32 s100, s100, 0x20000
	v_lshl_add_u32 v14, v8, 2, s100
	s_lshr_b32 s99, s34, 2
	s_branch .LBB0_768
.LBB0_766:
	s_or_b64 exec, exec, s[26:27]
	s_add_u32 s18, s18, s6
	v_add_u32_e32 v1, 0x400, v1
	s_addc_u32 s19, s19, s7
	v_add_u32_e32 v14, 0x400, v14
	s_xor_b32 s99, s99, 1
	s_mov_b64 s[26:27], 0

; #define PG8_LAS __attribute__((address_space(3)))
;     __host__ __device__ bool next(int i, Unit& u) const { if (i != 0 || c < 0 || c >= n) return false; u.pm = c / nN; u.pn = c - u.pm * nN; return true; }
; __device__ __forceinline__ float part8(const float* p) { const f32x4 a = *(const f32x4*)p, b = *(const f32x4*)(p + 4); return ((a[0] + a[1]) + (a[2] + a[3])) + ((b[0] + b[1]) + (b[2] + b[3])); }
;     __host__ __device__ bool next(int i, Unit& u) const {
;         const long L = (long)i * G + c; if (L >= nwg) return false;
;         int wgid = (int)L; { const int q = nwg / NXCD, r = nwg % NXCD, xcd = wgid % NXCD, off = wgid / NXCD; wgid = (xcd < r ? xcd * (q + 1) : r * (q + 1) + (xcd - r) * q) + off; }
;         const int nig = WGM * nN, gid = wgid / nig, fm = gid * WGM, gsz = (nM - fm) < WGM ? (nM - fm) : WGM;
;         u.pm = fm + ((wgid % nig) % gsz); u.pn = (wgid % nig) / gsz; return true;
;     template <class Sched> __device__ __forceinline__ void phase_init(const Sched& S, PG8_LAS float* tab, int tid) const {
;         Unit u;
;         for (int i = 0; S.next(i, u); ++i)
;             if (tid < 256) tab[i * 256 + tid] = __builtin_amdgcn_rsqf(part8(ssq + (size_t)(u.pm * BM + tid) * 8) * (1.0f / 2048.0f) + EPS);
;     }
.LBB0_768:
	v_cmp_gt_i64_e32 vcc, s[18:19], v[194:195]
	s_mov_b64 s[26:27], -1
	s_cbranch_vccnz .LBB0_767
	s_mov_b64 s[26:27], exec
	s_bitcmp1_b32 s99, 0
	s_cbranch_scc1 .LBB0_766
	s_ashr_i32 s8, s18, 31
	s_lshr_b32 s8, s8, 29
	s_add_i32 s8, s18, s8
	s_ashr_i32 s9, s8, 3
	s_and_b32 s8, s8, -8
	s_sub_i32 s8, s18, s8
	s_cmp_lt_i32 s8, 0
	s_movk_i32 s10, 0xb1
	s_cselect_b32 s10, s10, 0xb0
	s_mul_i32 s8, s8, s10
	s_add_i32 s8, s8, s9
	s_mul_hi_i32 s9, s8, 0x2e8ba2e9
	s_lshr_b32 s10, s9, 31
	s_ashr_i32 s9, s9, 6
	s_add_i32 s9, s9, s10
	s_lshl_b32 s10, s9, 3
	s_sub_i32 s11, 32, s10
	s_min_i32 s11, s11, 8
	s_abs_i32 s11, s11
	v_cvt_f32_u32_e32 v2, s11
	s_sub_i32 s12, 0, s11
	s_mulk_i32 s9, 0x160
	s_sub_i32 s8, s8, s9
	v_rcp_iflag_f32_e32 v2, v2
	s_ashr_i32 s9, s8, 31
	s_abs_i32 s8, s8
	v_mul_f32_e32 v2, 0x4f7ffffe, v2
	v_cvt_u32_f32_e32 v2, v2
	s_nop 0
	v_readfirstlane_b32 s13, v2
	s_mul_i32 s12, s12, s13
	s_mul_hi_u32 s12, s13, s12
	s_add_i32 s13, s13, s12
	s_mul_hi_u32 s12, s8, s13
	s_mul_i32 s12, s12, s11
	s_sub_i32 s8, s8, s12
	s_sub_i32 s12, s8, s11
	s_cmp_ge_u32 s8, s11
	s_cselect_b32 s8, s12, s8
	s_sub_i32 s12, s8, s11
	s_cmp_ge_u32 s8, s11
	s_cselect_b32 s8, s12, s8
	s_xor_b32 s8, s8, s9
	s_sub_i32 s8, s8, s9
	s_add_i32 s8, s8, s10
	v_lshl_add_u32 v2, s8, 8, v15
	v_ashrrev_i32_e32 v3, 31, v2
	v_lshlrev_b64 v[2:3], 5, v[2:3]
	v_lshl_add_u64 v[6:7], s[14:15], 0, v[2:3]
	flat_load_dwordx4 v[2:5], v[6:7]
	flat_load_dwordx4 v[10:13], v[6:7] offset:16
	s_waitcnt vmcnt(0) lgkmcnt(0)
	v_mov_b32_e32 v6, v2
	v_mov_b32_e32 v7, v10
	v_mov_b32_e32 v10, v3
	v_mov_b32_e32 v2, v4
	v_mov_b32_e32 v3, v12
	v_mov_b32_e32 v12, v5
	v_pk_add_f32 v[4:5], v[6:7], v[10:11]
	v_pk_add_f32 v[2:3], v[2:3], v[12:13]
	s_nop 0
	v_pk_add_f32 v[2:3], v[4:5], v[2:3]
	s_nop 0
	v_add_f32_e32 v2, v2, v3
	v_fmamk_f32 v2, v2, 0x3a000000, v220
	v_rsq_f32_e32 v2, v2
	ds_write_b32 v14, v2
	s_branch .LBB0_766
